# SwiGLU epilogue: row-scale waits made exact (vmcnt counts the younger prefetch DMA loads and earlier units' stores too: 22 instead of 14-2u), last tile waits once for all 16 loads; dtype comment added
# baseline (speedup 1.0000x reference)
; #define G_STAGE(bufoff, gbase, voff) do { _Pragma("unroll") for (int _i = 0; _i < 2; ++_i) \
;     __builtin_amdgcn_global_load_lds((const unsigned*)(uniform_ptr((const char*)(gbase)) + (voff)[_i]), (LAS unsigned*)(lds + (bufoff) + ldsw + _i * 8192), 16, 0, 0); } while (0)
;     ...
;   for (int u = (int)((blockIdx.x + gridDim.x - blk_off) % gridDim.x); u < nwg; u += gridDim.x) {
;     int wgid = u;
;     { int q = nwg / NXCD, r = nwg % NXCD, xcd = wgid % NXCD, off = wgid / NXCD; wgid = (xcd < r ? xcd * (q + 1) : r * (q + 1) + (xcd - r) * q) + off; }
;     int nig = WGM * nN, gid = wgid / nig, fm = gid * WGM, gsz = min(nM - fm, WGM);
;     const int pm = __builtin_amdgcn_readfirstlane(fm + ((wgid % nig) % gsz)), pn = __builtin_amdgcn_readfirstlane((wgid % nig) / gsz), brow = pm * BM, bcol = pn * BM;
;     f32x4 acc[2][2][4][2];
; #pragma unroll
;     for (int a = 0; a < 2; ++a)
; #pragma unroll
;       for (int b = 0; b < 2; ++b)
; #pragma unroll
;         for (int m = 0; m < 4; ++m)
; #pragma unroll
;           for (int n = 0; n < 2; ++n) acc[a][b][m][n] = (f32x4){0.f, 0.f, 0.f, 0.f};
;     bf16x8 At[4][2], B0[2][2], B1[2][2];
;     const char* cA = (const char*)A + (size_t)brow * lda * 2; const char* cB = (const char*)Bt + (size_t)bcol * ldb * 2;
;     G_STAGE(G_SB(0, 0), cB, voffB); G_STAGE(G_SA(0, 0), cA, voffA); G_STAGE(G_SB(0, 1), cB + hstepB, voffB); G_STAGE(G_SA(0, 1), cA + hstepA, voffA);
;   DI float rowscale(int row) const { const f32x4 a = *(const f32x4*)(ssp_in + (size_t)row * 8), b = *(const f32x4*)(ssp_in + (size_t)row * 8 + 4);
;     return rsqrtf((((a[0] + a[1]) + (a[2] + a[3])) + ((b[0] + b[1]) + (b[2] + b[3]))) * (1.f / D_) + EPS_); }
.LBB0_21:
	v_mov_b32_e32 v0, v199
	s_add_i32 s10, s10, s24
	s_mov_b32 s14, 0x800000
	v_and_or_b32 v136, v0, 15, s10
	v_ashrrev_i32_e32 v137, 31, v136
	v_lshlrev_b64 v[138:139], 5, v[136:137]
	v_lshl_add_u64 v[138:139], s[4:5], 0, v[138:139]
	s_mov_b64 s[100:101], 0x1000
	v_lshl_add_u64 v[240:241], v[138:139], 0, s[100:101]
	global_load_dwordx4 v[162:165], v[240:241], off offset:-4096
	global_load_dwordx4 v[166:169], v[240:241], off offset:-4080
	global_load_dwordx4 v[170:173], v[240:241], off offset:-3584
	global_load_dwordx4 v[174:177], v[240:241], off offset:-3568
	global_load_dwordx4 v[178:181], v[240:241], off offset:-3072
	global_load_dwordx4 v[182:185], v[240:241], off offset:-3056
	global_load_dwordx4 v[200:203], v[240:241], off offset:-2560
	global_load_dwordx4 v[204:207], v[240:241], off offset:-2544
	global_load_dwordx4 v[208:211], v[240:241], off
	global_load_dwordx4 v[212:215], v[240:241], off offset:16
	global_load_dwordx4 v[216:219], v[240:241], off offset:512
	global_load_dwordx4 v[220:223], v[240:241], off offset:528
	global_load_dwordx4 v[224:227], v[240:241], off offset:1024
	global_load_dwordx4 v[228:231], v[240:241], off offset:1040
	global_load_dwordx4 v[232:235], v[240:241], off offset:1536
	global_load_dwordx4 v[236:239], v[240:241], off offset:1552
	v_readlane_b32 s33, v250, 1
	s_add_i32 s33, s31, s33
	s_cmpk_gt_i32 s33, 0x57f
	s_cbranch_scc1 .Lpf_last
	s_ashr_i32 s34, s33, 31
	s_lshr_b32 s34, s34, 29
	s_add_i32 s34, s33, s34
	s_ashr_i32 s35, s34, 3
	s_and_b32 s34, s34, -8
	s_sub_i32 s34, s33, s34
	s_cmp_lt_i32 s34, 0
	s_movk_i32 s36, 0xb1
	s_cselect_b32 s36, s36, 0xb0
	s_mul_i32 s34, s36, s34
	s_add_i32 s34, s34, s35
	s_mul_hi_i32 s35, s34, 0x2e8ba2e9
	s_lshr_b32 s36, s35, 31
	s_ashr_i32 s35, s35, 6
	s_add_i32 s35, s35, s36
	s_lshl_b32 s36, s35, 3
	s_mulk_i32 s35, 0x160
	s_sub_i32 s34, s34, s35
	s_bfe_u32 s35, s34, 0x3001c
	s_add_i32 s35, s34, s35
	s_and_b32 s37, s35, 0xfff8
	s_sub_i32 s34, s34, s37
	s_sext_i32_i16 s34, s34
	s_sext_i32_i16 s35, s35
	s_add_i32 s36, s36, s34
	s_lshl_b32 s35, s35, 5
	s_lshl_b32 s34, s36, 8
	s_and_b32 s36, s35, 0xffffff00
	s_ashr_i32 s35, s34, 31
	s_ashr_i32 s37, s36, 31
	s_lshl_b64 s[18:19], s[34:35], 12
	s_lshl_b64 s[16:17], s[36:37], 12
	s_add_u32 s20, s22, s16
	s_addc_u32 s21, s23, s17
	v_readlane_b32 s100, v253, 54
	v_readlane_b32 s101, v253, 55
	s_add_u32 s100, s100, s18
	s_addc_u32 s101, s101, s19
	v_lshl_add_u64 v[242:243], s[20:21], 0, v[132:133]
	s_add_i32 m0, s26, 0x10000
	s_nop 0
	global_load_lds_dwordx4 v[242:243], off
	v_lshl_add_u64 v[242:243], s[20:21], 0, v[130:131]
	s_add_i32 m0, s26, 0x12000
	s_nop 0
	global_load_lds_dwordx4 v[242:243], off
	v_lshl_add_u64 v[242:243], s[100:101], 0, v[132:133]
	s_mov_b32 m0, s26
	s_nop 0
	global_load_lds_dwordx4 v[242:243], off
	v_lshl_add_u64 v[242:243], s[100:101], 0, v[130:131]
	s_add_i32 m0, s26, 0x2000
	s_nop 0
	global_load_lds_dwordx4 v[242:243], off
	s_add_u32 s36, s20, 0x80000
	s_addc_u32 s37, s21, 0
	v_lshl_add_u64 v[242:243], s[36:37], 0, v[132:133]
	s_add_i32 m0, s26, 0x14000
	s_nop 0
	global_load_lds_dwordx4 v[242:243], off
	v_lshl_add_u64 v[242:243], s[36:37], 0, v[130:131]
	s_add_i32 m0, s26, 0x16000
	s_nop 0
	global_load_lds_dwordx4 v[242:243], off
	s_add_u32 s36, s100, 0x80000
	s_addc_u32 s37, s101, 0
	v_lshl_add_u64 v[242:243], s[36:37], 0, v[132:133]
	s_add_i32 m0, s26, 0x4000
	s_nop 0
	global_load_lds_dwordx4 v[242:243], off
	v_lshl_add_u64 v[242:243], s[36:37], 0, v[130:131]
	s_add_i32 m0, s26, 0x6000
	s_nop 0
	global_load_lds_dwordx4 v[242:243], off
	s_branch .Lpf_skip

; DI float sigmoidf_(float x) { return frcp(1.f + __expf(-x)); }
; DI void st_bf16x4(bf16_t* p, f32x4 v) { u32x2 o; o.x = pk2e(v[0], v[1]); o.y = pk2e(v[2], v[3]); *(u32x2*)p = o; }
;   DI float operator()(int row, int colbase, int fq, f32x4 v0, f32x4 v1) const { one(row, colbase + 4 * fq, v0); one(row, colbase + 16 + 4 * fq, v1); return 0.f; }
;   DI float operator()(int row, int colbase, int fq, f32x4 v0, f32x4 v1) const { one(row, colbase + 4 * fq, v0); one(row, colbase + 16 + 4 * fq, v1); return 0.f; }
;   DI float operator()(int row, int colbase, int fq, f32x4 v0, f32x4 v1) const { one(row, colbase + 4 * fq, v0); one(row, colbase + 16 + 4 * fq, v1); return 0.f; }
;   DI float operator()(int row, int colbase, int fq, f32x4 v0, f32x4 v1) const { one(row, colbase + 4 * fq, v0); one(row, colbase + 16 + 4 * fq, v1); return 0.f; }
;     ...
;     for (int ai = 0; ai < 2; ++ai)
; #pragma unroll
;       for (int m = 0; m < 4; ++m) {
;         const int row = brow + ai * HALF + wr * 64 + m * 16 + fr_e;
;         const float rsc = epi.rowscale(row);
;         float ssq = 0.f;
; #pragma unroll
;         for (int bj = 0; bj < 2; ++bj)
;           ssq += epi(row, bcol + bj * HALF + wc * 32, fq_e, acc[ai][bj][m][0] * rsc, acc[ai][bj][m][1] * rsc);
;         rowss[ai][m] = ssq;
;   DI float rowscale(int row) const { const f32x4 a = *(const f32x4*)(ssp_in + (size_t)row * 8), b = *(const f32x4*)(ssp_in + (size_t)row * 8 + 4);
;     return rsqrtf((((a[0] + a[1]) + (a[2] + a[3])) + ((b[0] + b[1]) + (b[2] + b[3]))) * (1.f / D_) + EPS_); }
;   DI float operator()(int row, int colbase, int fq, f32x4 v0, f32x4 v1) const {
;     f32x4 r;
; #pragma unroll
;     for (int e = 0; e < 4; ++e) r[e] = v0[e] * sigmoidf_(v0[e]) * v1[e];
;     st_bf16x4(hid + (size_t)row * FFN_ + (colbase >> 1) + 4 * fq, r); return 0.f;
.Lpf_skip:
	v_lshrrev_b32_e32 v0, 1, v0
	v_and_b32_e32 v0, 24, v0
	v_lshl_add_u64 v[134:135], s[0:1], 0, v[0:1]
	s_or_b32 s10, s12, s25
	s_ashr_i32 s10, s10, 1
	s_movk_i32 s15, 0x2c00
	s_ashr_i32 s11, s10, 31
	s_lshl_b64 s[10:11], s[10:11], 1
	s_waitcnt vmcnt(22)
	v_mov_b32_e32 v138, v162
	v_mov_b32_e32 v139, v166
	v_mov_b32_e32 v166, v163
	v_mov_b32_e32 v162, v164
	v_mov_b32_e32 v163, v168
	v_mov_b32_e32 v168, v165
	v_pk_add_f32 v[138:139], v[138:139], v[166:167]
	v_pk_add_f32 v[162:163], v[162:163], v[168:169]
	s_nop 0
	v_pk_add_f32 v[138:139], v[138:139], v[162:163]
	s_nop 0
	v_add_f32_e32 v0, v138, v139
	v_fmamk_f32 v0, v0, 0x3a000000, v249
	v_cmp_gt_f32_e32 vcc, s14, v0
	v_mul_f32_e32 v137, 0x4b800000, v0
	v_mad_i64_i32 v[138:139], s[12:13], v136, s15, v[134:135]
	v_cndmask_b32_e32 v0, v0, v137, vcc
	v_rsq_f32_e32 v0, v0
	s_nop 0
	v_mul_f32_e32 v137, 0x45800000, v0
	v_cndmask_b32_e32 v0, v0, v137, vcc
	v_pk_mul_f32 v[122:123], v[122:123], v[0:1] op_sel_hi:[1,0]
	v_pk_mul_f32 v[124:125], v[124:125], v[0:1] op_sel_hi:[1,0]
	v_mul_f32_e32 v137, 0xbfb8aa3b, v122
	v_exp_f32_e32 v137, v137
	v_pk_mul_f32 v[126:127], v[126:127], v[0:1] op_sel_hi:[1,0]
	v_pk_mul_f32 v[118:119], v[118:119], v[0:1] op_sel_hi:[1,0]
	v_pk_mul_f32 v[128:129], v[128:129], v[0:1] op_sel_hi:[1,0]
	v_add_f32_e32 v137, 1.0, v137
	v_rcp_f32_e32 v142, v137
	v_mul_f32_e32 v137, 0xbfb8aa3b, v123
	v_exp_f32_e32 v137, v137
	v_pk_mul_f32 v[120:121], v[120:121], v[0:1] op_sel_hi:[1,0]
	v_pk_mul_f32 v[116:117], v[116:117], v[0:1] op_sel_hi:[1,0]
	v_pk_mul_f32 v[114:115], v[114:115], v[0:1] op_sel_hi:[1,0]
	v_add_f32_e32 v137, 1.0, v137
	v_rcp_f32_e32 v143, v137
	v_mul_f32_e32 v0, 0xbfb8aa3b, v118
	v_exp_f32_e32 v0, v0
	v_pk_mul_f32 v[122:123], v[122:123], v[142:143]
	s_nop 0
	v_pk_mul_f32 v[122:123], v[126:127], v[122:123]
	v_mul_f32_e32 v126, 0xbfb8aa3b, v124
	v_mul_f32_e32 v127, 0xbfb8aa3b, v125
	v_exp_f32_e32 v126, v126
	v_exp_f32_e32 v127, v127
	v_cvt_pk_bf16_f32 v122, v122, v123
	v_add_f32_e32 v0, 1.0, v0
	v_add_f32_e32 v126, 1.0, v126
	v_add_f32_e32 v127, 1.0, v127
	v_rcp_f32_e32 v126, v126
	v_rcp_f32_e32 v127, v127
	s_nop 0
	v_pk_mul_f32 v[124:125], v[124:125], v[126:127]
	s_nop 0
	v_pk_mul_f32 v[124:125], v[128:129], v[124:125]
	v_lshl_add_u64 v[126:127], v[138:139], 0, s[10:11]
	v_cvt_pk_bf16_f32 v123, v124, v125
	global_store_dwordx2 v[126:127], v[122:123], off
	v_rcp_f32_e32 v122, v0
	v_mul_f32_e32 v0, 0xbfb8aa3b, v119
	v_exp_f32_e32 v0, v0
	s_nop 0
	v_add_f32_e32 v0, 1.0, v0
	v_rcp_f32_e32 v123, v0
	v_mul_f32_e32 v0, 0xbfb8aa3b, v120
	v_exp_f32_e32 v0, v0
	v_pk_mul_f32 v[118:119], v[118:119], v[122:123]
	s_nop 0
	v_pk_mul_f32 v[114:115], v[114:115], v[118:119]
	v_add_f32_e32 v0, 1.0, v0
	v_rcp_f32_e32 v118, v0
	v_mul_f32_e32 v0, 0xbfb8aa3b, v121
	v_exp_f32_e32 v0, v0
	v_cvt_pk_bf16_f32 v114, v114, v115
	v_add_f32_e32 v0, 1.0, v0
	v_rcp_f32_e32 v119, v0
	s_nop 0
	v_pk_mul_f32 v[118:119], v[120:121], v[118:119]
	s_nop 0
	v_pk_mul_f32 v[116:117], v[116:117], v[118:119]
	s_nop 0
	v_cvt_pk_bf16_f32 v115, v116, v117
	global_store_dwordx2 v[126:127], v[114:115], off offset:128
	v_or_b32_e32 v122, 16, v136
	v_ashrrev_i32_e32 v123, 31, v122
	v_lshlrev_b64 v[114:115], 5, v[122:123]
	v_lshl_add_u64 v[118:119], s[4:5], 0, v[114:115]
	s_nop 0
	s_waitcnt vmcnt(22)
	v_mov_b32_e32 v124, v170
	v_mov_b32_e32 v125, v174
	v_mov_b32_e32 v174, v171
	v_pk_add_f32 v[170:171], v[124:125], v[174:175]
	v_mov_b32_e32 v174, v172
	v_mov_b32_e32 v175, v176
	v_mov_b32_e32 v176, v173
	v_pk_add_f32 v[172:173], v[174:175], v[176:177]
	s_nop 0
	v_pk_add_f32 v[170:171], v[170:171], v[172:173]
	s_nop 0
	v_add_f32_e32 v0, v170, v171
	v_fmamk_f32 v0, v0, 0x3a000000, v249
	v_cmp_gt_f32_e32 vcc, s14, v0
	v_mul_f32_e32 v114, 0x4b800000, v0
	s_nop 0
	v_cndmask_b32_e32 v0, v0, v114, vcc
	v_rsq_f32_e32 v0, v0
	s_nop 0
	v_mul_f32_e32 v114, 0x45800000, v0
	v_cndmask_b32_e32 v0, v0, v114, vcc
	v_pk_mul_f32 v[106:107], v[106:107], v[0:1] op_sel_hi:[1,0]
	v_pk_mul_f32 v[108:109], v[108:109], v[0:1] op_sel_hi:[1,0]
	v_mul_f32_e32 v116, 0xbfb8aa3b, v106
	v_mul_f32_e32 v117, 0xbfb8aa3b, v107
	v_exp_f32_e32 v116, v116
	v_exp_f32_e32 v117, v117
	v_pk_mul_f32 v[110:111], v[110:111], v[0:1] op_sel_hi:[1,0]
	v_pk_mul_f32 v[102:103], v[102:103], v[0:1] op_sel_hi:[1,0]
	v_add_f32_e32 v116, 1.0, v116
	v_add_f32_e32 v117, 1.0, v117
	v_rcp_f32_e32 v116, v116
	v_rcp_f32_e32 v117, v117
	v_pk_mul_f32 v[112:113], v[112:113], v[0:1] op_sel_hi:[1,0]
	v_pk_mul_f32 v[104:105], v[104:105], v[0:1] op_sel_hi:[1,0]
	v_pk_mul_f32 v[100:101], v[100:101], v[0:1] op_sel_hi:[1,0]
	v_pk_mul_f32 v[106:107], v[106:107], v[116:117]
	v_pk_mul_f32 v[98:99], v[98:99], v[0:1] op_sel_hi:[1,0]
	v_pk_mul_f32 v[110:111], v[110:111], v[106:107]
	v_mul_f32_e32 v106, 0xbfb8aa3b, v108
	v_mul_f32_e32 v107, 0xbfb8aa3b, v109
	v_exp_f32_e32 v106, v106
	v_exp_f32_e32 v107, v107
	v_mul_f32_e32 v0, 0xbfb8aa3b, v102
	v_exp_f32_e32 v0, v0
	v_add_f32_e32 v106, 1.0, v106
	v_add_f32_e32 v107, 1.0, v107
	v_rcp_f32_e32 v106, v106
	v_rcp_f32_e32 v107, v107
	v_add_f32_e32 v0, 1.0, v0
	v_cvt_pk_bf16_f32 v110, v110, v111
	v_mad_i64_i32 v[114:115], s[12:13], v122, s15, v[134:135]
	v_pk_mul_f32 v[106:107], v[108:109], v[106:107]
	s_nop 0
	v_pk_mul_f32 v[108:109], v[112:113], v[106:107]
	v_lshl_add_u64 v[106:107], v[114:115], 0, s[10:11]
	v_cvt_pk_bf16_f32 v111, v108, v109
	v_rcp_f32_e32 v108, v0
	v_mul_f32_e32 v0, 0xbfb8aa3b, v103
	v_exp_f32_e32 v0, v0
	global_store_dwordx2 v[106:107], v[110:111], off
	v_add_f32_e32 v0, 1.0, v0
	v_rcp_f32_e32 v109, v0
	v_mul_f32_e32 v0, 0xbfb8aa3b, v104
	v_exp_f32_e32 v0, v0
	v_pk_mul_f32 v[102:103], v[102:103], v[108:109]
	s_nop 0
	v_pk_mul_f32 v[98:99], v[98:99], v[102:103]
	v_add_f32_e32 v0, 1.0, v0
	v_rcp_f32_e32 v102, v0
	v_mul_f32_e32 v0, 0xbfb8aa3b, v105
	v_exp_f32_e32 v0, v0
	v_cvt_pk_bf16_f32 v98, v98, v99
	v_add_f32_e32 v0, 1.0, v0
	v_rcp_f32_e32 v103, v0
	s_nop 0
	v_pk_mul_f32 v[102:103], v[104:105], v[102:103]
	s_nop 0
	v_pk_mul_f32 v[100:101], v[100:101], v[102:103]
	s_nop 0
	v_cvt_pk_bf16_f32 v99, v100, v101
	global_store_dwordx2 v[106:107], v[98:99], off offset:128
	v_or_b32_e32 v106, 32, v136
	v_ashrrev_i32_e32 v107, 31, v106
	v_lshlrev_b64 v[98:99], 5, v[106:107]
	v_lshl_add_u64 v[102:103], s[4:5], 0, v[98:99]
	s_nop 0
	s_waitcnt vmcnt(22)
; DI float sigmoidf_(float x) { return frcp(1.f + __expf(-x)); }
; DI void st_bf16x4(bf16_t* p, f32x4 v) { u32x2 o; o.x = pk2e(v[0], v[1]); o.y = pk2e(v[2], v[3]); *(u32x2*)p = o; }
;   DI float operator()(int row, int colbase, int fq, f32x4 v0, f32x4 v1) const { one(row, colbase + 4 * fq, v0); one(row, colbase + 16 + 4 * fq, v1); return 0.f; }
;   DI float operator()(int row, int colbase, int fq, f32x4 v0, f32x4 v1) const { one(row, colbase + 4 * fq, v0); one(row, colbase + 16 + 4 * fq, v1); return 0.f; }
;   DI float operator()(int row, int colbase, int fq, f32x4 v0, f32x4 v1) const { one(row, colbase + 4 * fq, v0); one(row, colbase + 16 + 4 * fq, v1); return 0.f; }
;   DI float operator()(int row, int colbase, int fq, f32x4 v0, f32x4 v1) const { one(row, colbase + 4 * fq, v0); one(row, colbase + 16 + 4 * fq, v1); return 0.f; }
;     ...
;     for (int ai = 0; ai < 2; ++ai)
; #pragma unroll
;       for (int m = 0; m < 4; ++m) {
;         const int row = brow + ai * HALF + wr * 64 + m * 16 + fr_e;
;         const float rsc = epi.rowscale(row);
;         float ssq = 0.f;
; #pragma unroll
;         for (int bj = 0; bj < 2; ++bj)
;           ssq += epi(row, bcol + bj * HALF + wc * 32, fq_e, acc[ai][bj][m][0] * rsc, acc[ai][bj][m][1] * rsc);
;         rowss[ai][m] = ssq;
;   DI float rowscale(int row) const { const f32x4 a = *(const f32x4*)(ssp_in + (size_t)row * 8), b = *(const f32x4*)(ssp_in + (size_t)row * 8 + 4);
;     return rsqrtf((((a[0] + a[1]) + (a[2] + a[3])) + ((b[0] + b[1]) + (b[2] + b[3]))) * (1.f / D_) + EPS_); }
;   DI float operator()(int row, int colbase, int fq, f32x4 v0, f32x4 v1) const {
;     f32x4 r;
; #pragma unroll
;     for (int e = 0; e < 4; ++e) r[e] = v0[e] * sigmoidf_(v0[e]) * v1[e];
;     st_bf16x4(hid + (size_t)row * FFN_ + (colbase >> 1) + 4 * fq, r); return 0.f;
	v_mov_b32_e32 v108, v178
	v_mov_b32_e32 v109, v182
	v_mov_b32_e32 v182, v179
	v_pk_add_f32 v[178:179], v[108:109], v[182:183]
	v_mov_b32_e32 v182, v180
	v_mov_b32_e32 v183, v184
	v_mov_b32_e32 v184, v181
	v_pk_add_f32 v[180:181], v[182:183], v[184:185]
	s_nop 0
	v_pk_add_f32 v[178:179], v[178:179], v[180:181]
	s_nop 0
	v_add_f32_e32 v0, v178, v179
	v_fmamk_f32 v0, v0, 0x3a000000, v249
	v_cmp_gt_f32_e32 vcc, s14, v0
	v_mul_f32_e32 v98, 0x4b800000, v0
	s_nop 0
	v_cndmask_b32_e32 v0, v0, v98, vcc
	v_rsq_f32_e32 v0, v0
	s_nop 0
	v_mul_f32_e32 v98, 0x45800000, v0
	v_cndmask_b32_e32 v0, v0, v98, vcc
	v_pk_mul_f32 v[90:91], v[90:91], v[0:1] op_sel_hi:[1,0]
	v_pk_mul_f32 v[92:93], v[92:93], v[0:1] op_sel_hi:[1,0]
	v_mul_f32_e32 v100, 0xbfb8aa3b, v90
	v_mul_f32_e32 v101, 0xbfb8aa3b, v91
	v_exp_f32_e32 v100, v100
	v_exp_f32_e32 v101, v101
	v_pk_mul_f32 v[94:95], v[94:95], v[0:1] op_sel_hi:[1,0]
	v_pk_mul_f32 v[86:87], v[86:87], v[0:1] op_sel_hi:[1,0]
	v_add_f32_e32 v100, 1.0, v100
	v_add_f32_e32 v101, 1.0, v101
	v_rcp_f32_e32 v100, v100
	v_rcp_f32_e32 v101, v101
	v_pk_mul_f32 v[96:97], v[96:97], v[0:1] op_sel_hi:[1,0]
	v_pk_mul_f32 v[88:89], v[88:89], v[0:1] op_sel_hi:[1,0]
	v_pk_mul_f32 v[84:85], v[84:85], v[0:1] op_sel_hi:[1,0]
	v_pk_mul_f32 v[90:91], v[90:91], v[100:101]
	v_pk_mul_f32 v[82:83], v[82:83], v[0:1] op_sel_hi:[1,0]
	v_pk_mul_f32 v[94:95], v[94:95], v[90:91]
	v_mul_f32_e32 v90, 0xbfb8aa3b, v92
	v_mul_f32_e32 v91, 0xbfb8aa3b, v93
	v_exp_f32_e32 v90, v90
	v_exp_f32_e32 v91, v91
	v_mul_f32_e32 v0, 0xbfb8aa3b, v86
	v_exp_f32_e32 v0, v0
	v_add_f32_e32 v90, 1.0, v90
	v_add_f32_e32 v91, 1.0, v91
	v_rcp_f32_e32 v90, v90
	v_rcp_f32_e32 v91, v91
	v_add_f32_e32 v0, 1.0, v0
	v_cvt_pk_bf16_f32 v94, v94, v95
	v_mad_i64_i32 v[98:99], s[12:13], v106, s15, v[134:135]
	v_pk_mul_f32 v[90:91], v[92:93], v[90:91]
	s_nop 0
	v_pk_mul_f32 v[92:93], v[96:97], v[90:91]
	v_lshl_add_u64 v[90:91], v[98:99], 0, s[10:11]
	v_cvt_pk_bf16_f32 v95, v92, v93
	v_rcp_f32_e32 v92, v0
	v_mul_f32_e32 v0, 0xbfb8aa3b, v87
	v_exp_f32_e32 v0, v0
	global_store_dwordx2 v[90:91], v[94:95], off
	v_add_f32_e32 v0, 1.0, v0
	v_rcp_f32_e32 v93, v0
	v_mul_f32_e32 v0, 0xbfb8aa3b, v88
	v_exp_f32_e32 v0, v0
	v_pk_mul_f32 v[86:87], v[86:87], v[92:93]
	s_nop 0
	v_pk_mul_f32 v[82:83], v[82:83], v[86:87]
	v_add_f32_e32 v0, 1.0, v0
	v_rcp_f32_e32 v86, v0
	v_mul_f32_e32 v0, 0xbfb8aa3b, v89
	v_exp_f32_e32 v0, v0
	v_cvt_pk_bf16_f32 v82, v82, v83
	v_add_f32_e32 v0, 1.0, v0
	v_rcp_f32_e32 v87, v0
	s_nop 0
	v_pk_mul_f32 v[86:87], v[88:89], v[86:87]
	s_nop 0
	v_pk_mul_f32 v[84:85], v[84:85], v[86:87]
	s_nop 0
	v_cvt_pk_bf16_f32 v83, v84, v85
	global_store_dwordx2 v[90:91], v[82:83], off offset:128
	v_or_b32_e32 v90, 48, v136
	v_ashrrev_i32_e32 v91, 31, v90
	v_lshlrev_b64 v[82:83], 5, v[90:91]
	v_lshl_add_u64 v[86:87], s[4:5], 0, v[82:83]
	s_nop 0
	s_waitcnt vmcnt(22)
	v_mov_b32_e32 v92, v200
	v_mov_b32_e32 v93, v204
	v_mov_b32_e32 v204, v201
	v_pk_add_f32 v[200:201], v[92:93], v[204:205]
	v_mov_b32_e32 v204, v202
	v_mov_b32_e32 v205, v206
	v_mov_b32_e32 v206, v203
	v_pk_add_f32 v[202:203], v[204:205], v[206:207]
	s_nop 0
	v_pk_add_f32 v[200:201], v[200:201], v[202:203]
	s_nop 0
	v_add_f32_e32 v0, v200, v201
	v_fmamk_f32 v0, v0, 0x3a000000, v249
	v_cmp_gt_f32_e32 vcc, s14, v0
	v_mul_f32_e32 v82, 0x4b800000, v0
	s_nop 0
	v_cndmask_b32_e32 v0, v0, v82, vcc
	v_rsq_f32_e32 v0, v0
	s_nop 0
	v_mul_f32_e32 v82, 0x45800000, v0
	v_cndmask_b32_e32 v0, v0, v82, vcc
	v_pk_mul_f32 v[74:75], v[74:75], v[0:1] op_sel_hi:[1,0]
	v_pk_mul_f32 v[76:77], v[76:77], v[0:1] op_sel_hi:[1,0]
	v_mul_f32_e32 v84, 0xbfb8aa3b, v74
	v_mul_f32_e32 v85, 0xbfb8aa3b, v75
	v_exp_f32_e32 v84, v84
	v_exp_f32_e32 v85, v85
	v_pk_mul_f32 v[78:79], v[78:79], v[0:1] op_sel_hi:[1,0]
	v_pk_mul_f32 v[70:71], v[70:71], v[0:1] op_sel_hi:[1,0]
	v_add_f32_e32 v84, 1.0, v84
	v_add_f32_e32 v85, 1.0, v85
	v_rcp_f32_e32 v84, v84
	v_rcp_f32_e32 v85, v85
	v_pk_mul_f32 v[80:81], v[80:81], v[0:1] op_sel_hi:[1,0]
	v_pk_mul_f32 v[72:73], v[72:73], v[0:1] op_sel_hi:[1,0]
	v_pk_mul_f32 v[68:69], v[68:69], v[0:1] op_sel_hi:[1,0]
	v_pk_mul_f32 v[74:75], v[74:75], v[84:85]
	v_pk_mul_f32 v[66:67], v[66:67], v[0:1] op_sel_hi:[1,0]
	v_pk_mul_f32 v[78:79], v[78:79], v[74:75]
	v_mul_f32_e32 v74, 0xbfb8aa3b, v76
	v_mul_f32_e32 v75, 0xbfb8aa3b, v77
	v_exp_f32_e32 v74, v74
	v_exp_f32_e32 v75, v75
	v_mul_f32_e32 v0, 0xbfb8aa3b, v70
	v_exp_f32_e32 v0, v0
	v_add_f32_e32 v74, 1.0, v74
	v_add_f32_e32 v75, 1.0, v75
	v_rcp_f32_e32 v74, v74
	v_rcp_f32_e32 v75, v75
	v_add_f32_e32 v0, 1.0, v0
	v_cvt_pk_bf16_f32 v78, v78, v79
	v_mad_i64_i32 v[82:83], s[12:13], v90, s15, v[134:135]
	v_pk_mul_f32 v[74:75], v[76:77], v[74:75]
	s_nop 0
	v_pk_mul_f32 v[76:77], v[80:81], v[74:75]
	v_lshl_add_u64 v[74:75], v[82:83], 0, s[10:11]
	v_cvt_pk_bf16_f32 v79, v76, v77
	v_rcp_f32_e32 v76, v0
	v_mul_f32_e32 v0, 0xbfb8aa3b, v71
	v_exp_f32_e32 v0, v0
	global_store_dwordx2 v[74:75], v[78:79], off
	v_add_f32_e32 v0, 1.0, v0
	v_rcp_f32_e32 v77, v0
	v_mul_f32_e32 v0, 0xbfb8aa3b, v72
	v_exp_f32_e32 v0, v0
	v_pk_mul_f32 v[70:71], v[70:71], v[76:77]
	s_nop 0
	v_pk_mul_f32 v[66:67], v[66:67], v[70:71]
	v_add_f32_e32 v0, 1.0, v0
	v_rcp_f32_e32 v70, v0
	v_mul_f32_e32 v0, 0xbfb8aa3b, v73
	v_exp_f32_e32 v0, v0
	v_cvt_pk_bf16_f32 v66, v66, v67
	v_add_f32_e32 v0, 1.0, v0
	v_rcp_f32_e32 v71, v0
	s_nop 0
	v_pk_mul_f32 v[70:71], v[72:73], v[70:71]
	s_nop 0
	v_pk_mul_f32 v[68:69], v[68:69], v[70:71]
	s_nop 0
	v_cvt_pk_bf16_f32 v67, v68, v69
	global_store_dwordx2 v[74:75], v[66:67], off offset:128
	v_add_u32_e32 v74, 0x80, v136
	v_ashrrev_i32_e32 v75, 31, v74
	v_lshlrev_b64 v[66:67], 5, v[74:75]
	v_lshl_add_u64 v[70:71], s[4:5], 0, v[66:67]
	s_nop 0
	s_waitcnt vmcnt(22)
; DI float sigmoidf_(float x) { return frcp(1.f + __expf(-x)); }
; DI void st_bf16x4(bf16_t* p, f32x4 v) { u32x2 o; o.x = pk2e(v[0], v[1]); o.y = pk2e(v[2], v[3]); *(u32x2*)p = o; }
;   DI float operator()(int row, int colbase, int fq, f32x4 v0, f32x4 v1) const { one(row, colbase + 4 * fq, v0); one(row, colbase + 16 + 4 * fq, v1); return 0.f; }
;   DI float operator()(int row, int colbase, int fq, f32x4 v0, f32x4 v1) const { one(row, colbase + 4 * fq, v0); one(row, colbase + 16 + 4 * fq, v1); return 0.f; }
;   DI float operator()(int row, int colbase, int fq, f32x4 v0, f32x4 v1) const { one(row, colbase + 4 * fq, v0); one(row, colbase + 16 + 4 * fq, v1); return 0.f; }
;   DI float operator()(int row, int colbase, int fq, f32x4 v0, f32x4 v1) const { one(row, colbase + 4 * fq, v0); one(row, colbase + 16 + 4 * fq, v1); return 0.f; }
;     ...
;     for (int ai = 0; ai < 2; ++ai)
; #pragma unroll
;       for (int m = 0; m < 4; ++m) {
;         const int row = brow + ai * HALF + wr * 64 + m * 16 + fr_e;
;         const float rsc = epi.rowscale(row);
;         float ssq = 0.f;
; #pragma unroll
;         for (int bj = 0; bj < 2; ++bj)
;           ssq += epi(row, bcol + bj * HALF + wc * 32, fq_e, acc[ai][bj][m][0] * rsc, acc[ai][bj][m][1] * rsc);
;         rowss[ai][m] = ssq;
;   DI float rowscale(int row) const { const f32x4 a = *(const f32x4*)(ssp_in + (size_t)row * 8), b = *(const f32x4*)(ssp_in + (size_t)row * 8 + 4);
;     return rsqrtf((((a[0] + a[1]) + (a[2] + a[3])) + ((b[0] + b[1]) + (b[2] + b[3]))) * (1.f / D_) + EPS_); }
;   DI float operator()(int row, int colbase, int fq, f32x4 v0, f32x4 v1) const {
;     f32x4 r;
; #pragma unroll
;     for (int e = 0; e < 4; ++e) r[e] = v0[e] * sigmoidf_(v0[e]) * v1[e];
;     st_bf16x4(hid + (size_t)row * FFN_ + (colbase >> 1) + 4 * fq, r); return 0.f;
	v_mov_b32_e32 v76, v208
	v_mov_b32_e32 v77, v212
	v_mov_b32_e32 v212, v209
	v_pk_add_f32 v[208:209], v[76:77], v[212:213]
	v_mov_b32_e32 v212, v210
	v_mov_b32_e32 v213, v214
	v_mov_b32_e32 v214, v211
	v_pk_add_f32 v[210:211], v[212:213], v[214:215]
	s_nop 0
	v_pk_add_f32 v[208:209], v[208:209], v[210:211]
	s_nop 0
	v_add_f32_e32 v0, v208, v209
	v_fmamk_f32 v0, v0, 0x3a000000, v249
	v_cmp_gt_f32_e32 vcc, s14, v0
	v_mul_f32_e32 v66, 0x4b800000, v0
	s_nop 0
	v_cndmask_b32_e32 v0, v0, v66, vcc
	v_rsq_f32_e32 v0, v0
	s_nop 0
	v_mul_f32_e32 v66, 0x45800000, v0
	v_cndmask_b32_e32 v0, v0, v66, vcc
	v_pk_mul_f32 v[58:59], v[58:59], v[0:1] op_sel_hi:[1,0]
	v_pk_mul_f32 v[60:61], v[60:61], v[0:1] op_sel_hi:[1,0]
	v_mul_f32_e32 v68, 0xbfb8aa3b, v58
	v_mul_f32_e32 v69, 0xbfb8aa3b, v59
	v_exp_f32_e32 v68, v68
	v_exp_f32_e32 v69, v69
	v_pk_mul_f32 v[62:63], v[62:63], v[0:1] op_sel_hi:[1,0]
	v_pk_mul_f32 v[54:55], v[54:55], v[0:1] op_sel_hi:[1,0]
	v_add_f32_e32 v68, 1.0, v68
	v_add_f32_e32 v69, 1.0, v69
	v_rcp_f32_e32 v68, v68
	v_rcp_f32_e32 v69, v69
	v_pk_mul_f32 v[64:65], v[64:65], v[0:1] op_sel_hi:[1,0]
	v_pk_mul_f32 v[56:57], v[56:57], v[0:1] op_sel_hi:[1,0]
	v_pk_mul_f32 v[52:53], v[52:53], v[0:1] op_sel_hi:[1,0]
	v_pk_mul_f32 v[58:59], v[58:59], v[68:69]
	v_pk_mul_f32 v[50:51], v[50:51], v[0:1] op_sel_hi:[1,0]
	v_pk_mul_f32 v[62:63], v[62:63], v[58:59]
	v_mul_f32_e32 v58, 0xbfb8aa3b, v60
	v_mul_f32_e32 v59, 0xbfb8aa3b, v61
	v_exp_f32_e32 v58, v58
	v_exp_f32_e32 v59, v59
	v_mul_f32_e32 v0, 0xbfb8aa3b, v54
	v_exp_f32_e32 v0, v0
	v_add_f32_e32 v58, 1.0, v58
	v_add_f32_e32 v59, 1.0, v59
	v_rcp_f32_e32 v58, v58
	v_rcp_f32_e32 v59, v59
	v_add_f32_e32 v0, 1.0, v0
	v_cvt_pk_bf16_f32 v62, v62, v63
	v_mad_i64_i32 v[66:67], s[12:13], v74, s15, v[134:135]
	v_pk_mul_f32 v[58:59], v[60:61], v[58:59]
	s_nop 0
	v_pk_mul_f32 v[60:61], v[64:65], v[58:59]
	v_lshl_add_u64 v[58:59], v[66:67], 0, s[10:11]
	v_cvt_pk_bf16_f32 v63, v60, v61
	v_rcp_f32_e32 v60, v0
	v_mul_f32_e32 v0, 0xbfb8aa3b, v55
	v_exp_f32_e32 v0, v0
	global_store_dwordx2 v[58:59], v[62:63], off
	v_add_f32_e32 v0, 1.0, v0
	v_rcp_f32_e32 v61, v0
	v_mul_f32_e32 v0, 0xbfb8aa3b, v56
	v_exp_f32_e32 v0, v0
	v_pk_mul_f32 v[54:55], v[54:55], v[60:61]
	s_nop 0
	v_pk_mul_f32 v[50:51], v[50:51], v[54:55]
	v_add_f32_e32 v0, 1.0, v0
	v_rcp_f32_e32 v54, v0
	v_mul_f32_e32 v0, 0xbfb8aa3b, v57
	v_exp_f32_e32 v0, v0
	v_cvt_pk_bf16_f32 v50, v50, v51
	v_add_f32_e32 v0, 1.0, v0
	v_rcp_f32_e32 v55, v0
	s_nop 0
	v_pk_mul_f32 v[54:55], v[56:57], v[54:55]
	s_nop 0
	v_pk_mul_f32 v[52:53], v[52:53], v[54:55]
	s_nop 0
	v_cvt_pk_bf16_f32 v51, v52, v53
	global_store_dwordx2 v[58:59], v[50:51], off offset:128
	v_add_u32_e32 v58, 0x90, v136
	v_ashrrev_i32_e32 v59, 31, v58
	v_lshlrev_b64 v[50:51], 5, v[58:59]
	v_lshl_add_u64 v[54:55], s[4:5], 0, v[50:51]
	s_nop 0
	s_waitcnt vmcnt(22)
	v_mov_b32_e32 v60, v216
	v_mov_b32_e32 v61, v220
	v_mov_b32_e32 v220, v217
	v_pk_add_f32 v[216:217], v[60:61], v[220:221]
	v_mov_b32_e32 v220, v218
	v_mov_b32_e32 v221, v222
	v_mov_b32_e32 v222, v219
	v_pk_add_f32 v[218:219], v[220:221], v[222:223]
	s_nop 0
	v_pk_add_f32 v[216:217], v[216:217], v[218:219]
	s_nop 0
	v_add_f32_e32 v0, v216, v217
	v_fmamk_f32 v0, v0, 0x3a000000, v249
	v_cmp_gt_f32_e32 vcc, s14, v0
	v_mul_f32_e32 v50, 0x4b800000, v0
	s_nop 0
	v_cndmask_b32_e32 v0, v0, v50, vcc
	v_rsq_f32_e32 v0, v0
	s_nop 0
	v_mul_f32_e32 v50, 0x45800000, v0
	v_cndmask_b32_e32 v0, v0, v50, vcc
	v_pk_mul_f32 v[42:43], v[42:43], v[0:1] op_sel_hi:[1,0]
	v_pk_mul_f32 v[44:45], v[44:45], v[0:1] op_sel_hi:[1,0]
	v_mul_f32_e32 v52, 0xbfb8aa3b, v42
	v_mul_f32_e32 v53, 0xbfb8aa3b, v43
	v_exp_f32_e32 v52, v52
	v_exp_f32_e32 v53, v53
	v_pk_mul_f32 v[46:47], v[46:47], v[0:1] op_sel_hi:[1,0]
	v_pk_mul_f32 v[38:39], v[38:39], v[0:1] op_sel_hi:[1,0]
	v_add_f32_e32 v52, 1.0, v52
	v_add_f32_e32 v53, 1.0, v53
	v_rcp_f32_e32 v52, v52
	v_rcp_f32_e32 v53, v53
	v_pk_mul_f32 v[48:49], v[48:49], v[0:1] op_sel_hi:[1,0]
	v_pk_mul_f32 v[40:41], v[40:41], v[0:1] op_sel_hi:[1,0]
	v_pk_mul_f32 v[36:37], v[36:37], v[0:1] op_sel_hi:[1,0]
	v_pk_mul_f32 v[42:43], v[42:43], v[52:53]
	v_pk_mul_f32 v[34:35], v[34:35], v[0:1] op_sel_hi:[1,0]
	v_pk_mul_f32 v[46:47], v[46:47], v[42:43]
	v_mul_f32_e32 v42, 0xbfb8aa3b, v44
	v_mul_f32_e32 v43, 0xbfb8aa3b, v45
	v_exp_f32_e32 v42, v42
	v_exp_f32_e32 v43, v43
	v_mul_f32_e32 v0, 0xbfb8aa3b, v38
	v_exp_f32_e32 v0, v0
	v_add_f32_e32 v42, 1.0, v42
	v_add_f32_e32 v43, 1.0, v43
	v_rcp_f32_e32 v42, v42
	v_rcp_f32_e32 v43, v43
	v_add_f32_e32 v0, 1.0, v0
	v_cvt_pk_bf16_f32 v46, v46, v47
	v_mad_i64_i32 v[50:51], s[12:13], v58, s15, v[134:135]
	v_pk_mul_f32 v[42:43], v[44:45], v[42:43]
	s_nop 0
	v_pk_mul_f32 v[44:45], v[48:49], v[42:43]
	v_lshl_add_u64 v[42:43], v[50:51], 0, s[10:11]
	v_cvt_pk_bf16_f32 v47, v44, v45
	v_rcp_f32_e32 v44, v0
	v_mul_f32_e32 v0, 0xbfb8aa3b, v39
	v_exp_f32_e32 v0, v0
	global_store_dwordx2 v[42:43], v[46:47], off
	v_add_f32_e32 v0, 1.0, v0
	v_rcp_f32_e32 v45, v0
	v_mul_f32_e32 v0, 0xbfb8aa3b, v40
	v_exp_f32_e32 v0, v0
	v_pk_mul_f32 v[38:39], v[38:39], v[44:45]
	s_nop 0
	v_pk_mul_f32 v[34:35], v[34:35], v[38:39]
	v_add_f32_e32 v0, 1.0, v0
	v_rcp_f32_e32 v38, v0
	v_mul_f32_e32 v0, 0xbfb8aa3b, v41
	v_exp_f32_e32 v0, v0
	v_cvt_pk_bf16_f32 v34, v34, v35
	v_add_f32_e32 v0, 1.0, v0
	v_rcp_f32_e32 v39, v0
	s_nop 0
	v_pk_mul_f32 v[38:39], v[40:41], v[38:39]
	s_nop 0
	v_pk_mul_f32 v[36:37], v[36:37], v[38:39]
	s_nop 0
	v_cvt_pk_bf16_f32 v35, v36, v37
	global_store_dwordx2 v[42:43], v[34:35], off offset:128
	v_add_u32_e32 v42, 0xa0, v136
	v_ashrrev_i32_e32 v43, 31, v42
	v_lshlrev_b64 v[34:35], 5, v[42:43]
	v_lshl_add_u64 v[38:39], s[4:5], 0, v[34:35]
	s_nop 0
	s_waitcnt vmcnt(22)
; DI float sigmoidf_(float x) { return frcp(1.f + __expf(-x)); }
; DI void st_bf16x4(bf16_t* p, f32x4 v) { u32x2 o; o.x = pk2e(v[0], v[1]); o.y = pk2e(v[2], v[3]); *(u32x2*)p = o; }
;   DI float operator()(int row, int colbase, int fq, f32x4 v0, f32x4 v1) const { one(row, colbase + 4 * fq, v0); one(row, colbase + 16 + 4 * fq, v1); return 0.f; }
;   DI float operator()(int row, int colbase, int fq, f32x4 v0, f32x4 v1) const { one(row, colbase + 4 * fq, v0); one(row, colbase + 16 + 4 * fq, v1); return 0.f; }
;   DI float operator()(int row, int colbase, int fq, f32x4 v0, f32x4 v1) const { one(row, colbase + 4 * fq, v0); one(row, colbase + 16 + 4 * fq, v1); return 0.f; }
;   DI float operator()(int row, int colbase, int fq, f32x4 v0, f32x4 v1) const { one(row, colbase + 4 * fq, v0); one(row, colbase + 16 + 4 * fq, v1); return 0.f; }
;     ...
;   for (int u = (int)((blockIdx.x + gridDim.x - blk_off) % gridDim.x); u < nwg; u += gridDim.x) {
;     ...
;     for (int ai = 0; ai < 2; ++ai)
; #pragma unroll
;       for (int m = 0; m < 4; ++m) {
;         const int row = brow + ai * HALF + wr * 64 + m * 16 + fr_e;
;         const float rsc = epi.rowscale(row);
;         float ssq = 0.f;
; #pragma unroll
;         for (int bj = 0; bj < 2; ++bj)
;           ssq += epi(row, bcol + bj * HALF + wc * 32, fq_e, acc[ai][bj][m][0] * rsc, acc[ai][bj][m][1] * rsc);
;         rowss[ai][m] = ssq;
;     ...
;     __syncthreads();
;   DI float rowscale(int row) const { const f32x4 a = *(const f32x4*)(ssp_in + (size_t)row * 8), b = *(const f32x4*)(ssp_in + (size_t)row * 8 + 4);
;     return rsqrtf((((a[0] + a[1]) + (a[2] + a[3])) + ((b[0] + b[1]) + (b[2] + b[3]))) * (1.f / D_) + EPS_); }
;   DI float operator()(int row, int colbase, int fq, f32x4 v0, f32x4 v1) const {
;     f32x4 r;
; #pragma unroll
;     for (int e = 0; e < 4; ++e) r[e] = v0[e] * sigmoidf_(v0[e]) * v1[e];
;     st_bf16x4(hid + (size_t)row * FFN_ + (colbase >> 1) + 4 * fq, r); return 0.f;
	v_mov_b32_e32 v44, v224
	v_mov_b32_e32 v45, v228
	v_mov_b32_e32 v228, v225
	v_pk_add_f32 v[224:225], v[44:45], v[228:229]
	v_mov_b32_e32 v228, v226
	v_mov_b32_e32 v229, v230
	v_mov_b32_e32 v230, v227
	v_pk_add_f32 v[226:227], v[228:229], v[230:231]
	s_nop 0
	v_pk_add_f32 v[224:225], v[224:225], v[226:227]
	s_nop 0
	v_add_f32_e32 v0, v224, v225
	v_fmamk_f32 v0, v0, 0x3a000000, v249
	v_cmp_gt_f32_e32 vcc, s14, v0
	v_mul_f32_e32 v34, 0x4b800000, v0
	s_nop 0
	v_cndmask_b32_e32 v0, v0, v34, vcc
	v_rsq_f32_e32 v0, v0
	s_nop 0
	v_mul_f32_e32 v34, 0x45800000, v0
	v_cndmask_b32_e32 v0, v0, v34, vcc
	v_pk_mul_f32 v[26:27], v[26:27], v[0:1] op_sel_hi:[1,0]
	v_pk_mul_f32 v[28:29], v[28:29], v[0:1] op_sel_hi:[1,0]
	v_mul_f32_e32 v36, 0xbfb8aa3b, v26
	v_mul_f32_e32 v37, 0xbfb8aa3b, v27
	v_exp_f32_e32 v36, v36
	v_exp_f32_e32 v37, v37
	v_pk_mul_f32 v[30:31], v[30:31], v[0:1] op_sel_hi:[1,0]
	v_pk_mul_f32 v[22:23], v[22:23], v[0:1] op_sel_hi:[1,0]
	v_add_f32_e32 v36, 1.0, v36
	v_add_f32_e32 v37, 1.0, v37
	v_rcp_f32_e32 v36, v36
	v_rcp_f32_e32 v37, v37
	v_pk_mul_f32 v[32:33], v[32:33], v[0:1] op_sel_hi:[1,0]
	v_pk_mul_f32 v[24:25], v[24:25], v[0:1] op_sel_hi:[1,0]
	v_pk_mul_f32 v[20:21], v[20:21], v[0:1] op_sel_hi:[1,0]
	v_pk_mul_f32 v[26:27], v[26:27], v[36:37]
	v_pk_mul_f32 v[18:19], v[18:19], v[0:1] op_sel_hi:[1,0]
	v_pk_mul_f32 v[30:31], v[30:31], v[26:27]
	v_mul_f32_e32 v26, 0xbfb8aa3b, v28
	v_mul_f32_e32 v27, 0xbfb8aa3b, v29
	v_exp_f32_e32 v26, v26
	v_exp_f32_e32 v27, v27
	v_mul_f32_e32 v0, 0xbfb8aa3b, v22
	v_exp_f32_e32 v0, v0
	v_add_f32_e32 v26, 1.0, v26
	v_add_f32_e32 v27, 1.0, v27
	v_rcp_f32_e32 v26, v26
	v_rcp_f32_e32 v27, v27
	v_add_f32_e32 v0, 1.0, v0
	v_cvt_pk_bf16_f32 v30, v30, v31
	v_mad_i64_i32 v[34:35], s[12:13], v42, s15, v[134:135]
	v_pk_mul_f32 v[26:27], v[28:29], v[26:27]
	s_nop 0
	v_pk_mul_f32 v[28:29], v[32:33], v[26:27]
	v_lshl_add_u64 v[26:27], v[34:35], 0, s[10:11]
	v_cvt_pk_bf16_f32 v31, v28, v29
	v_rcp_f32_e32 v28, v0
	v_mul_f32_e32 v0, 0xbfb8aa3b, v23
	v_exp_f32_e32 v0, v0
	global_store_dwordx2 v[26:27], v[30:31], off
	v_add_f32_e32 v0, 1.0, v0
	v_rcp_f32_e32 v29, v0
	v_mul_f32_e32 v0, 0xbfb8aa3b, v24
	v_exp_f32_e32 v0, v0
	v_pk_mul_f32 v[22:23], v[22:23], v[28:29]
	s_nop 0
	v_pk_mul_f32 v[18:19], v[18:19], v[22:23]
	v_add_f32_e32 v0, 1.0, v0
	v_rcp_f32_e32 v22, v0
	v_mul_f32_e32 v0, 0xbfb8aa3b, v25
	v_exp_f32_e32 v0, v0
	v_cvt_pk_bf16_f32 v18, v18, v19
	v_add_f32_e32 v0, 1.0, v0
	v_rcp_f32_e32 v23, v0
	s_nop 0
	v_pk_mul_f32 v[22:23], v[24:25], v[22:23]
	s_nop 0
	v_pk_mul_f32 v[20:21], v[20:21], v[22:23]
	s_nop 0
	v_cvt_pk_bf16_f32 v19, v20, v21
	global_store_dwordx2 v[26:27], v[18:19], off offset:128
	v_add_u32_e32 v26, 0xb0, v136
	v_ashrrev_i32_e32 v27, 31, v26
	v_lshlrev_b64 v[18:19], 5, v[26:27]
	v_lshl_add_u64 v[22:23], s[4:5], 0, v[18:19]
	s_nop 0
	s_mov_b32 s84, 0x800000
	s_waitcnt vmcnt(22)
	v_mov_b32_e32 v28, v232
	v_mov_b32_e32 v29, v236
	v_mov_b32_e32 v236, v233
	v_pk_add_f32 v[232:233], v[28:29], v[236:237]
	v_mov_b32_e32 v236, v234
	v_mov_b32_e32 v237, v238
	v_mov_b32_e32 v238, v235
	v_pk_add_f32 v[234:235], v[236:237], v[238:239]
	s_nop 0
	v_pk_add_f32 v[232:233], v[232:233], v[234:235]
	s_nop 0
	v_add_f32_e32 v0, v232, v233
	v_fmamk_f32 v0, v0, 0x3a000000, v249
	v_cmp_gt_f32_e32 vcc, s14, v0
	v_mul_f32_e32 v18, 0x4b800000, v0
	s_nop 0
	v_cndmask_b32_e32 v0, v0, v18, vcc
	v_rsq_f32_e32 v0, v0
	s_nop 0
	v_mul_f32_e32 v18, 0x45800000, v0
	v_cndmask_b32_e32 v0, v0, v18, vcc
	v_pk_mul_f32 v[10:11], v[10:11], v[0:1] op_sel_hi:[1,0]
	v_pk_mul_f32 v[12:13], v[12:13], v[0:1] op_sel_hi:[1,0]
	v_mul_f32_e32 v20, 0xbfb8aa3b, v10
	v_mul_f32_e32 v21, 0xbfb8aa3b, v11
	v_exp_f32_e32 v20, v20
	v_exp_f32_e32 v21, v21
	v_pk_mul_f32 v[14:15], v[14:15], v[0:1] op_sel_hi:[1,0]
	v_pk_mul_f32 v[6:7], v[6:7], v[0:1] op_sel_hi:[1,0]
	v_add_f32_e32 v20, 1.0, v20
	v_add_f32_e32 v21, 1.0, v21
	v_rcp_f32_e32 v20, v20
	v_rcp_f32_e32 v21, v21
	v_pk_mul_f32 v[16:17], v[16:17], v[0:1] op_sel_hi:[1,0]
	v_pk_mul_f32 v[8:9], v[8:9], v[0:1] op_sel_hi:[1,0]
	v_pk_mul_f32 v[4:5], v[4:5], v[0:1] op_sel_hi:[1,0]
	v_pk_mul_f32 v[10:11], v[10:11], v[20:21]
	v_pk_mul_f32 v[2:3], v[2:3], v[0:1] op_sel_hi:[1,0]
	v_pk_mul_f32 v[14:15], v[14:15], v[10:11]
	v_mul_f32_e32 v10, 0xbfb8aa3b, v12
	v_mul_f32_e32 v11, 0xbfb8aa3b, v13
	v_exp_f32_e32 v10, v10
	v_exp_f32_e32 v11, v11
	v_mul_f32_e32 v0, 0xbfb8aa3b, v6
	v_exp_f32_e32 v0, v0
	v_add_f32_e32 v10, 1.0, v10
	v_add_f32_e32 v11, 1.0, v11
	v_rcp_f32_e32 v10, v10
	v_rcp_f32_e32 v11, v11
	v_add_f32_e32 v0, 1.0, v0
	v_cvt_pk_bf16_f32 v14, v14, v15
	v_mad_i64_i32 v[18:19], s[12:13], v26, s15, v[134:135]
	v_pk_mul_f32 v[10:11], v[12:13], v[10:11]
	s_nop 0
	v_pk_mul_f32 v[12:13], v[16:17], v[10:11]
	v_lshl_add_u64 v[10:11], v[18:19], 0, s[10:11]
	v_cvt_pk_bf16_f32 v15, v12, v13
	v_rcp_f32_e32 v12, v0
	v_mul_f32_e32 v0, 0xbfb8aa3b, v7
	v_exp_f32_e32 v0, v0
	global_store_dwordx2 v[10:11], v[14:15], off
	v_add_f32_e32 v0, 1.0, v0
	v_rcp_f32_e32 v13, v0
	v_mul_f32_e32 v0, 0xbfb8aa3b, v8
	v_exp_f32_e32 v0, v0
	v_pk_mul_f32 v[6:7], v[6:7], v[12:13]
	s_nop 0
	v_pk_mul_f32 v[2:3], v[2:3], v[6:7]
	v_add_f32_e32 v0, 1.0, v0
	v_rcp_f32_e32 v6, v0
	v_mul_f32_e32 v0, 0xbfb8aa3b, v9
	v_exp_f32_e32 v0, v0
	v_cvt_pk_bf16_f32 v2, v2, v3
	v_add_f32_e32 v0, 1.0, v0
	v_rcp_f32_e32 v7, v0
	s_nop 0
	v_pk_mul_f32 v[6:7], v[8:9], v[6:7]
	s_nop 0
	v_pk_mul_f32 v[4:5], v[4:5], v[6:7]
	s_nop 0
	v_cvt_pk_bf16_f32 v3, v4, v5
	global_store_dwordx2 v[10:11], v[2:3], off offset:128
	v_readlane_b32 s10, v250, 1
	s_add_i32 s31, s31, s10
	s_cmpk_gt_i32 s31, 0x57f
	s_barrier
	v_readlane_b32 s11, v250, 2
	s_cbranch_scc1 .LBB0_31
	s_branch .Lpf_setup
